# v25 + P0 weight conversion groups 0/1 hand-rewritten (all 32 loads of a transposing item in flight)
# speedup vs baseline: 1.0129x; 1.0129x over previous
.LBB0_7:
	s_or_b64 exec, exec, s[2:3]
	s_load_dwordx16 s[36:51], s[0:1], 0x40
	s_load_dwordx16 s[4:19], s[0:1], 0x80
	s_lshr_b32 s83, s80, 6
	s_cmp_lt_i32 s90, 1
	s_waitcnt lgkmcnt(0)
	v_writelane_b32 v255, s4, 7
	s_nop 1
	v_writelane_b32 v255, s5, 8
	v_writelane_b32 v255, s6, 9
	v_writelane_b32 v255, s7, 10
	v_writelane_b32 v255, s8, 11
	v_writelane_b32 v255, s9, 12
	v_writelane_b32 v255, s10, 13
	v_writelane_b32 v255, s11, 14
	v_writelane_b32 v255, s12, 15
	v_writelane_b32 v255, s13, 16
	v_writelane_b32 v255, s14, 17
	v_writelane_b32 v255, s15, 18
	v_writelane_b32 v255, s16, 19
	v_writelane_b32 v255, s17, 20
	v_writelane_b32 v255, s18, 21
	v_writelane_b32 v255, s19, 22
	s_load_dwordx16 s[4:19], s[0:1], 0xc0
	s_cselect_b64 s[0:1], -1, 0
	s_cmp_gt_i32 s91, 0
	s_cselect_b64 s[2:3], -1, 0
	s_and_b64 s[0:1], s[0:1], s[2:3]
	s_waitcnt lgkmcnt(0)
	v_writelane_b32 v255, s4, 23
	s_andn2_b64 vcc, exec, s[0:1]
	s_nop 0
	v_writelane_b32 v255, s5, 24
	v_writelane_b32 v255, s6, 25
	v_writelane_b32 v255, s7, 26
	v_writelane_b32 v255, s8, 27
	v_writelane_b32 v255, s9, 28
	v_writelane_b32 v255, s10, 29
	v_writelane_b32 v255, s11, 30
	v_writelane_b32 v255, s12, 31
	v_writelane_b32 v255, s13, 32
	v_writelane_b32 v255, s14, 33
	v_writelane_b32 v255, s15, 34
	v_writelane_b32 v255, s16, 35
	v_writelane_b32 v255, s17, 36
	v_writelane_b32 v255, s18, 37
	v_writelane_b32 v255, s19, 38
	v_writelane_b32 v255, s80, 39
	v_writelane_b32 v255, s36, 40
	s_nop 1
	v_writelane_b32 v255, s37, 41
	v_writelane_b32 v255, s38, 42
	v_writelane_b32 v255, s39, 43
	v_writelane_b32 v255, s40, 44
	v_writelane_b32 v255, s41, 45
	v_writelane_b32 v255, s42, 46
	v_writelane_b32 v255, s43, 47
	v_writelane_b32 v255, s44, 48
	v_writelane_b32 v255, s45, 49
	v_writelane_b32 v255, s46, 50
	v_writelane_b32 v255, s47, 51
	v_writelane_b32 v255, s48, 52
	v_writelane_b32 v255, s49, 53
	v_writelane_b32 v255, s50, 54
	v_writelane_b32 v255, s51, 55
	s_cbranch_vccnz .LBB0_105
	s_lshl_b32 s0, s82, 3
	s_add_i32 s2, s0, s83
	s_lshl_b32 s4, s33, 3
	s_cmp_gt_i32 s82, -1
	v_mbcnt_lo_u32_b32 v6, -1, 0
	v_mbcnt_hi_u32_b32 v6, -1, v6
	s_cbranch_scc0 .LBB0_41
	s_mov_b32 s6, s2
	s_mov_b32 s7, s4
	v_mov_b32_e32 v100, v6
	v_and_b32_e32 v101, 31, v100
	v_lshrrev_b32_e32 v102, 5, v100
	s_lshl_b32 s8, s83, 14
	v_mad_u32_u24 v103, v102, 33, v101
	v_lshl_add_u32 v103, v103, 2, s8
	v_and_b32_e32 v104, 7, v100
	v_lshrrev_b32_e32 v105, 3, v100
	v_mul_u32_u24_e32 v106, 0x108, v104
	v_add_u32_e32 v106, v106, v105
	v_lshl_add_u32 v106, v106, 2, s8
.Lcv0_item:
	s_cmpk_lt_u32 s6, 2816
	s_cbranch_scc0 .Lcv0_win
	s_mul_i32 s1, s6, 5958
	s_lshr_b32 s1, s1, 20
	s_mul_i32 s3, s1, 176
	s_sub_i32 s3, s6, s3
	s_lshl_b32 s18, s3, 5
	s_lshl_b32 s17, s1, 6
	s_cmpk_lt_u32 s18, 2816
	s_cselect_b32 s3, 0, 2816
	s_cselect_b32 s5, 0, 128
	s_sub_i32 s3, s18, s3
	s_lshr_b32 s16, s3, 7
	s_lshl_b32 s16, s16, 8
	s_and_b32 s3, s3, 127
	s_add_i32 s16, s16, s3
	s_add_i32 s16, s16, s5
	s_mov_b64 s[10:11], s[36:37]
	s_movk_i32 s12, 5632
	s_movk_i32 s13, 1024
	s_add_u32 s14, s26, 0x200000
	s_addc_u32 s15, s27, 0
	s_branch .Lcv0_go
.Lcv0_win:
	s_cmpk_lt_u32 s6, 4480
	s_cbranch_scc0 .Lcv0_w2
	s_sub_i32 s1, s6, 2816
	s_mul_i32 s3, s1, 10083
	s_lshr_b32 s3, s3, 20
	s_mul_i32 s5, s3, 104
	s_sub_i32 s1, s1, s5
	s_lshl_b32 s18, s1, 5
	s_lshl_b32 s17, s3, 6
	s_mov_b32 s16, s18
	s_mov_b64 s[10:11], s[44:45]
	s_movk_i32 s12, 3328
	s_movk_i32 s13, 1024
	s_add_u32 s14, s26, 0x2600000
	s_addc_u32 s15, s27, 0
	s_branch .Lcv0_go
.Lcv0_w2:
	s_cmpk_lt_u32 s6, 4496
	s_cbranch_scc0 .Lcv0_a2
	s_sub_i32 s1, s6, 4480
	s_lshl_b32 s18, s1, 5
	s_mov_b32 s17, 0
	s_mov_b32 s16, s18
	v_readlane_b32 s10, v255, 19
	v_readlane_b32 s11, v255, 20
	s_movk_i32 s12, 512
	s_movk_i32 s13, 64
	s_add_u32 s14, s26, 0x2f00000
	s_addc_u32 s15, s27, 0
	s_branch .Lcv0_go
.Lcv0_a2:
	s_cmpk_lt_u32 s6, 4512
	s_cbranch_scc0 .Lcv0_g2
	s_sub_i32 s1, s6, 4496
	s_lshl_b32 s18, s1, 5
	s_mov_b32 s17, 0
	s_mov_b32 s16, s18
	v_readlane_b32 s10, v255, 23
	v_readlane_b32 s11, v255, 24
	s_movk_i32 s12, 512
	s_movk_i32 s13, 64
	s_add_u32 s14, s26, 0x2f10000
	s_addc_u32 s15, s27, 0
	s_branch .Lcv0_go
.Lcv0_g2:
	s_sub_i32 s1, s6, 4512
	s_lshr_b32 s3, s1, 4
	s_and_b32 s1, s1, 15
	s_lshl_b32 s18, s1, 5
	s_lshl_b32 s17, s3, 6
	s_mov_b32 s16, s18
	v_readlane_b32 s10, v255, 25
	v_readlane_b32 s11, v255, 26
	s_movk_i32 s12, 512
	s_movk_i32 s13, 128
	s_add_u32 s14, s26, 0x2f20000
	s_addc_u32 s15, s27, 0
.Lcv0_go:
	s_mul_i32 s1, s17, s12
	s_add_i32 s1, s1, s18
	s_lshl_b32 s1, s1, 2
	s_nop 3
	s_add_u32 s10, s10, s1
	s_addc_u32 s11, s11, 0
	v_mul_lo_u32 v107, v102, s12
	v_add_lshl_u32 v107, v107, v101, 2
	s_lshl_b32 s19, s12, 3
	global_load_dword v16, v107, s[10:11]
	s_add_u32 s10, s10, s19
	s_addc_u32 s11, s11, 0
	global_load_dword v17, v107, s[10:11]
	s_add_u32 s10, s10, s19
	s_addc_u32 s11, s11, 0
	global_load_dword v18, v107, s[10:11]
	s_add_u32 s10, s10, s19
	s_addc_u32 s11, s11, 0
	global_load_dword v19, v107, s[10:11]
	s_add_u32 s10, s10, s19
	s_addc_u32 s11, s11, 0
	global_load_dword v20, v107, s[10:11]
	s_add_u32 s10, s10, s19
	s_addc_u32 s11, s11, 0
	global_load_dword v21, v107, s[10:11]
	s_add_u32 s10, s10, s19
	s_addc_u32 s11, s11, 0
	global_load_dword v22, v107, s[10:11]
	s_add_u32 s10, s10, s19
	s_addc_u32 s11, s11, 0
	global_load_dword v23, v107, s[10:11]
	s_add_u32 s10, s10, s19
	s_addc_u32 s11, s11, 0
	global_load_dword v24, v107, s[10:11]
	s_add_u32 s10, s10, s19
	s_addc_u32 s11, s11, 0
	global_load_dword v25, v107, s[10:11]
	s_add_u32 s10, s10, s19
	s_addc_u32 s11, s11, 0
	global_load_dword v26, v107, s[10:11]
	s_add_u32 s10, s10, s19
	s_addc_u32 s11, s11, 0
	global_load_dword v27, v107, s[10:11]
	s_add_u32 s10, s10, s19
	s_addc_u32 s11, s11, 0
	global_load_dword v28, v107, s[10:11]
	s_add_u32 s10, s10, s19
	s_addc_u32 s11, s11, 0
	global_load_dword v29, v107, s[10:11]
	s_add_u32 s10, s10, s19
	s_addc_u32 s11, s11, 0
	global_load_dword v30, v107, s[10:11]
	s_add_u32 s10, s10, s19
	s_addc_u32 s11, s11, 0
	global_load_dword v31, v107, s[10:11]
	s_add_u32 s10, s10, s19
	s_addc_u32 s11, s11, 0
	global_load_dword v32, v107, s[10:11]
	s_add_u32 s10, s10, s19
	s_addc_u32 s11, s11, 0
	global_load_dword v33, v107, s[10:11]
	s_add_u32 s10, s10, s19
	s_addc_u32 s11, s11, 0
	global_load_dword v34, v107, s[10:11]
	s_add_u32 s10, s10, s19
	s_addc_u32 s11, s11, 0
	global_load_dword v35, v107, s[10:11]
	s_add_u32 s10, s10, s19
	s_addc_u32 s11, s11, 0
	global_load_dword v36, v107, s[10:11]
	s_add_u32 s10, s10, s19
	s_addc_u32 s11, s11, 0
	global_load_dword v37, v107, s[10:11]
	s_add_u32 s10, s10, s19
	s_addc_u32 s11, s11, 0
	global_load_dword v38, v107, s[10:11]
	s_add_u32 s10, s10, s19
	s_addc_u32 s11, s11, 0
	global_load_dword v39, v107, s[10:11]
	s_add_u32 s10, s10, s19
	s_addc_u32 s11, s11, 0
	global_load_dword v40, v107, s[10:11]
	s_add_u32 s10, s10, s19
	s_addc_u32 s11, s11, 0
	global_load_dword v41, v107, s[10:11]
	s_add_u32 s10, s10, s19
	s_addc_u32 s11, s11, 0
	global_load_dword v42, v107, s[10:11]
	s_add_u32 s10, s10, s19
	s_addc_u32 s11, s11, 0
	global_load_dword v43, v107, s[10:11]
	s_add_u32 s10, s10, s19
	s_addc_u32 s11, s11, 0
	global_load_dword v44, v107, s[10:11]
	s_add_u32 s10, s10, s19
	s_addc_u32 s11, s11, 0
	global_load_dword v45, v107, s[10:11]
	s_add_u32 s10, s10, s19
	s_addc_u32 s11, s11, 0
	global_load_dword v46, v107, s[10:11]
	s_add_u32 s10, s10, s19
	s_addc_u32 s11, s11, 0
	global_load_dword v47, v107, s[10:11]
	s_mul_i32 s1, s16, s13
	s_add_i32 s1, s1, s17
	s_lshl_b32 s1, s1, 1
	s_add_u32 s14, s14, s1
	s_addc_u32 s15, s15, 0
	v_mul_lo_u32 v108, v105, s13
	v_lshl_add_u32 v80, v104, 3, v108
	v_lshlrev_b32_e32 v108, 1, v80
	s_lshl_b32 s19, s13, 4
	s_waitcnt vmcnt(31)
	ds_write_b32 v103, v16 offset:0
	s_waitcnt vmcnt(30)
	ds_write_b32 v103, v17 offset:264
	s_waitcnt vmcnt(29)
	ds_write_b32 v103, v18 offset:528
	s_waitcnt vmcnt(28)
	ds_write_b32 v103, v19 offset:792
	s_waitcnt vmcnt(27)
	ds_write_b32 v103, v20 offset:1056
	s_waitcnt vmcnt(26)
	ds_write_b32 v103, v21 offset:1320
	s_waitcnt vmcnt(25)
	ds_write_b32 v103, v22 offset:1584
	s_waitcnt vmcnt(24)
	ds_write_b32 v103, v23 offset:1848
	s_waitcnt vmcnt(23)
	ds_write_b32 v103, v24 offset:2112
	s_waitcnt vmcnt(22)
	ds_write_b32 v103, v25 offset:2376
	s_waitcnt vmcnt(21)
	ds_write_b32 v103, v26 offset:2640
	s_waitcnt vmcnt(20)
	ds_write_b32 v103, v27 offset:2904
	s_waitcnt vmcnt(19)
	ds_write_b32 v103, v28 offset:3168
	s_waitcnt vmcnt(18)
	ds_write_b32 v103, v29 offset:3432
	s_waitcnt vmcnt(17)
	ds_write_b32 v103, v30 offset:3696
	s_waitcnt vmcnt(16)
	ds_write_b32 v103, v31 offset:3960
	s_waitcnt vmcnt(15)
	ds_write_b32 v103, v32 offset:4224
	s_waitcnt vmcnt(14)
	ds_write_b32 v103, v33 offset:4488
	s_waitcnt vmcnt(13)
	ds_write_b32 v103, v34 offset:4752
	s_waitcnt vmcnt(12)
	ds_write_b32 v103, v35 offset:5016
	s_waitcnt vmcnt(11)
	ds_write_b32 v103, v36 offset:5280
	s_waitcnt vmcnt(10)
	ds_write_b32 v103, v37 offset:5544
	s_waitcnt vmcnt(9)
	ds_write_b32 v103, v38 offset:5808
	s_waitcnt vmcnt(8)
	ds_write_b32 v103, v39 offset:6072
	s_waitcnt vmcnt(7)
	ds_write_b32 v103, v40 offset:6336
	s_waitcnt vmcnt(6)
	ds_write_b32 v103, v41 offset:6600
	s_waitcnt vmcnt(5)
	ds_write_b32 v103, v42 offset:6864
	s_waitcnt vmcnt(4)
	ds_write_b32 v103, v43 offset:7128
	s_waitcnt vmcnt(3)
	ds_write_b32 v103, v44 offset:7392
	s_waitcnt vmcnt(2)
	ds_write_b32 v103, v45 offset:7656
	s_waitcnt vmcnt(1)
	ds_write_b32 v103, v46 offset:7920
	s_waitcnt vmcnt(0)
	ds_write_b32 v103, v47 offset:8184
	s_waitcnt lgkmcnt(0)
	ds_read_b32 v48, v106 offset:0
	ds_read_b32 v49, v106 offset:132
	ds_read_b32 v50, v106 offset:264
	ds_read_b32 v51, v106 offset:396
	ds_read_b32 v52, v106 offset:528
	ds_read_b32 v53, v106 offset:660
	ds_read_b32 v54, v106 offset:792
	ds_read_b32 v55, v106 offset:924
	s_waitcnt lgkmcnt(0)
	v_cvt_pk_bf16_f32 v80, v48, v49
	v_cvt_pk_bf16_f32 v81, v50, v51
	v_cvt_pk_bf16_f32 v82, v52, v53
	v_cvt_pk_bf16_f32 v83, v54, v55
	global_store_dwordx4 v108, v[80:83], s[14:15]
	s_add_u32 s14, s14, s19
	s_addc_u32 s15, s15, 0
	ds_read_b32 v56, v106 offset:32
	ds_read_b32 v57, v106 offset:164
	ds_read_b32 v58, v106 offset:296
	ds_read_b32 v59, v106 offset:428
	ds_read_b32 v60, v106 offset:560
	ds_read_b32 v61, v106 offset:692
	ds_read_b32 v62, v106 offset:824
	ds_read_b32 v63, v106 offset:956
	s_waitcnt lgkmcnt(0)
	v_cvt_pk_bf16_f32 v84, v56, v57
	v_cvt_pk_bf16_f32 v85, v58, v59
	v_cvt_pk_bf16_f32 v86, v60, v61
	v_cvt_pk_bf16_f32 v87, v62, v63
	global_store_dwordx4 v108, v[84:87], s[14:15]
	s_add_u32 s14, s14, s19
	s_addc_u32 s15, s15, 0
	ds_read_b32 v64, v106 offset:64
	ds_read_b32 v65, v106 offset:196
	ds_read_b32 v66, v106 offset:328
	ds_read_b32 v67, v106 offset:460
	ds_read_b32 v68, v106 offset:592
	ds_read_b32 v69, v106 offset:724
	ds_read_b32 v70, v106 offset:856
	ds_read_b32 v71, v106 offset:988
	s_waitcnt lgkmcnt(0)
	v_cvt_pk_bf16_f32 v88, v64, v65
	v_cvt_pk_bf16_f32 v89, v66, v67
	v_cvt_pk_bf16_f32 v90, v68, v69
	v_cvt_pk_bf16_f32 v91, v70, v71
	global_store_dwordx4 v108, v[88:91], s[14:15]
	s_add_u32 s14, s14, s19
	s_addc_u32 s15, s15, 0
	ds_read_b32 v72, v106 offset:96
	ds_read_b32 v73, v106 offset:228
	ds_read_b32 v74, v106 offset:360
	ds_read_b32 v75, v106 offset:492
	ds_read_b32 v76, v106 offset:624
	ds_read_b32 v77, v106 offset:756
	ds_read_b32 v78, v106 offset:888
	ds_read_b32 v79, v106 offset:1020
	s_waitcnt lgkmcnt(0)
	v_cvt_pk_bf16_f32 v92, v72, v73
	v_cvt_pk_bf16_f32 v93, v74, v75
	v_cvt_pk_bf16_f32 v94, v76, v77
	v_cvt_pk_bf16_f32 v95, v78, v79
	global_store_dwordx4 v108, v[92:95], s[14:15]
	s_add_i32 s6, s6, s7
	s_cmpk_lt_u32 s6, 4544
	s_cbranch_scc1 .Lcv0_item
